# speedup vs baseline: 1.0081x; 1.0014x over previous
;   DEVINL void operator()(Acc& acc, int brow, int bcol) const {
;     ...
;     } else if (tt >= 16 && tt < 18) {
;       _Pragma("unroll") for (int ai = 0; ai < 2; ++ai) _Pragma("unroll") for (int bj = 0; bj < 2; ++bj) _Pragma("unroll") for (int m = 0; m < 4; ++m) _Pragma("unroll") for (int n = 0; n < 2; ++n) {
;         const int row0 = brow + ai * 128 + wr * 64 + m * 16 + fq * 4;
;         const int head = (tt - 16) * 4 + wc, d = fr * 4 + bj * 2 + n;
;         const f32x4 v = acc[ai][bj][m][n];
;         *(bf16x4*)(P.vnT + ((size_t)(row0 >> 6) * 512 + head * 64 + d) * 64 + (row0 & 63)) = pack4(v[0], v[1], v[2], v[3]);
;       }
.LBB0_757:
	s_and_b64 vcc, exec, s[8:9]
	s_cbranch_vccz .LBB0_759
	s_load_dwordx2 s[8:9], s[88:89], 0x1c8
	v_and_b32_e32 v184, 63, v147
	v_lshrrev_b32_e32 v185, 6, v147
	v_and_b32_e32 v186, 3, v185
	v_mul_u32_u24_e32 v186, 0x1200, v186
	v_lshrrev_b32_e32 v187, 2, v185
	v_lshl_add_u32 v186, v187, 16, v186
	v_add_u32_e32 v186, 0x8000, v186
	v_mul_u32_u24_e32 v188, 0x120, v146
	v_lshl_add_u32 v188, v145, 3, v188
	v_add_u32_e32 v188, v188, v186
	v_lshrrev_b32_e32 v189, 3, v184
	v_mul_u32_u24_e32 v189, 0x90, v189
	v_and_b32_e32 v190, 7, v184
	v_lshl_add_u32 v189, v190, 4, v189
	v_add_u32_e32 v189, v189, v186
	s_lshr_b32 s10, s12, 6
	s_lshl_b32 s10, s10, 16
	s_add_i32 s11, s37, -16
	s_lshl_b32 s11, s11, 15
	s_add_i32 s10, s10, s11
	v_lshlrev_b32_e32 v191, 13, v149
	v_lshl_add_u32 v191, v144, 16, v191
	v_lshl_add_u32 v191, v190, 4, v191
	v_lshrrev_b32_e32 v192, 4, v184
	v_lshl_add_u32 v191, v192, 9, v191
	v_bfe_u32 v192, v184, 3, 1
	v_lshl_add_u32 v191, v192, 7, v191
	v_add_u32_e32 v191, s10, v191
	v_cvt_pk_bf16_f32 v194, v118, v119
	v_cvt_pk_bf16_f32 v195, v120, v121
	ds_write_b64 v188, v[194:195]
	v_cvt_pk_bf16_f32 v196, v114, v115
	v_cvt_pk_bf16_f32 v197, v116, v117
	ds_write_b64 v188, v[196:197] offset:144
	v_cvt_pk_bf16_f32 v198, v102, v103
	v_cvt_pk_bf16_f32 v199, v104, v105
	ds_write_b64 v188, v[198:199] offset:32
	v_cvt_pk_bf16_f32 v200, v98, v99
	v_cvt_pk_bf16_f32 v201, v100, v101
	ds_write_b64 v188, v[200:201] offset:176
	v_cvt_pk_bf16_f32 v202, v86, v87
	v_cvt_pk_bf16_f32 v203, v88, v89
	ds_write_b64 v188, v[202:203] offset:64
	v_cvt_pk_bf16_f32 v204, v82, v83
	v_cvt_pk_bf16_f32 v205, v84, v85
	ds_write_b64 v188, v[204:205] offset:208
	v_cvt_pk_bf16_f32 v206, v70, v71
	v_cvt_pk_bf16_f32 v207, v72, v73
	ds_write_b64 v188, v[206:207] offset:96
	v_cvt_pk_bf16_f32 v208, v66, v67
	v_cvt_pk_bf16_f32 v209, v68, v69
	ds_write_b64 v188, v[208:209] offset:240
	ds_read_b128 v[210:213], v189
	ds_read_b128 v[214:217], v189 offset:1152
	ds_read_b128 v[218:221], v189 offset:2304
	ds_read_b128 v[222:225], v189 offset:3456
	s_waitcnt lgkmcnt(0)
	v_add_u32_e32 v193, 0x0, v191
	global_store_dwordx4 v193, v[210:213], s[8:9]
	v_add_u32_e32 v193, 0x800, v191
	global_store_dwordx4 v193, v[214:217], s[8:9]
	v_add_u32_e32 v193, 0x1000, v191
	global_store_dwordx4 v193, v[218:221], s[8:9]
	v_add_u32_e32 v193, 0x1800, v191
	global_store_dwordx4 v193, v[222:225], s[8:9]
	v_cvt_pk_bf16_f32 v194, v126, v127
	v_cvt_pk_bf16_f32 v195, v128, v129
	ds_write_b64 v188, v[194:195]
	v_cvt_pk_bf16_f32 v196, v122, v123
	v_cvt_pk_bf16_f32 v197, v124, v125
	ds_write_b64 v188, v[196:197] offset:144
	v_cvt_pk_bf16_f32 v198, v110, v111
	v_cvt_pk_bf16_f32 v199, v112, v113
	ds_write_b64 v188, v[198:199] offset:32
	v_cvt_pk_bf16_f32 v200, v106, v107
	v_cvt_pk_bf16_f32 v201, v108, v109
	ds_write_b64 v188, v[200:201] offset:176
	v_cvt_pk_bf16_f32 v202, v94, v95
	v_cvt_pk_bf16_f32 v203, v96, v97
	ds_write_b64 v188, v[202:203] offset:64
	v_cvt_pk_bf16_f32 v204, v90, v91
	v_cvt_pk_bf16_f32 v205, v92, v93
	ds_write_b64 v188, v[204:205] offset:208
	v_cvt_pk_bf16_f32 v206, v78, v79
	v_cvt_pk_bf16_f32 v207, v80, v81
	ds_write_b64 v188, v[206:207] offset:96
	v_cvt_pk_bf16_f32 v208, v74, v75
	v_cvt_pk_bf16_f32 v209, v76, v77
	ds_write_b64 v188, v[208:209] offset:240
	ds_read_b128 v[152:155], v189
	ds_read_b128 v[156:159], v189 offset:1152
	ds_read_b128 v[160:163], v189 offset:2304
	ds_read_b128 v[164:167], v189 offset:3456
	s_waitcnt lgkmcnt(3)
	v_add_u32_e32 v193, 0x0, v191
	global_store_dwordx4 v193, v[152:155], s[8:9] offset:256
	s_waitcnt lgkmcnt(2)
	v_add_u32_e32 v193, 0x800, v191
	global_store_dwordx4 v193, v[156:159], s[8:9] offset:256
	s_waitcnt lgkmcnt(1)
	v_add_u32_e32 v193, 0x1000, v191
	global_store_dwordx4 v193, v[160:163], s[8:9] offset:256
	s_waitcnt lgkmcnt(0)
	v_add_u32_e32 v193, 0x1800, v191
	global_store_dwordx4 v193, v[164:167], s[8:9] offset:256
	v_cvt_pk_bf16_f32 v194, v54, v55
	v_cvt_pk_bf16_f32 v195, v56, v57
	ds_write_b64 v188, v[194:195]
	v_cvt_pk_bf16_f32 v196, v50, v51
	v_cvt_pk_bf16_f32 v197, v52, v53
	ds_write_b64 v188, v[196:197] offset:144
	v_cvt_pk_bf16_f32 v198, v38, v39
	v_cvt_pk_bf16_f32 v199, v40, v41
	ds_write_b64 v188, v[198:199] offset:32
	v_cvt_pk_bf16_f32 v200, v34, v35
	v_cvt_pk_bf16_f32 v201, v36, v37
	ds_write_b64 v188, v[200:201] offset:176
	v_cvt_pk_bf16_f32 v202, v22, v23
	v_cvt_pk_bf16_f32 v203, v24, v25
	ds_write_b64 v188, v[202:203] offset:64
	v_cvt_pk_bf16_f32 v204, v18, v19
	v_cvt_pk_bf16_f32 v205, v20, v21
	ds_write_b64 v188, v[204:205] offset:208
	v_cvt_pk_bf16_f32 v206, v6, v7
	v_cvt_pk_bf16_f32 v207, v8, v9
	ds_write_b64 v188, v[206:207] offset:96
	v_cvt_pk_bf16_f32 v208, v2, v3
	v_cvt_pk_bf16_f32 v209, v4, v5
	ds_write_b64 v188, v[208:209] offset:240
	ds_read_b128 v[210:213], v189
	ds_read_b128 v[214:217], v189 offset:1152
	ds_read_b128 v[218:221], v189 offset:2304
	ds_read_b128 v[222:225], v189 offset:3456
	s_waitcnt lgkmcnt(3)
	v_add_u32_e32 v193, 0x20000, v191
	global_store_dwordx4 v193, v[210:213], s[8:9]
	s_waitcnt lgkmcnt(2)
	v_add_u32_e32 v193, 0x20800, v191
	global_store_dwordx4 v193, v[214:217], s[8:9]
	s_waitcnt lgkmcnt(1)
	v_add_u32_e32 v193, 0x21000, v191
	global_store_dwordx4 v193, v[218:221], s[8:9]
	s_waitcnt lgkmcnt(0)
	v_add_u32_e32 v193, 0x21800, v191
	global_store_dwordx4 v193, v[222:225], s[8:9]
	v_cvt_pk_bf16_f32 v194, v62, v63
	v_cvt_pk_bf16_f32 v195, v64, v65
	ds_write_b64 v188, v[194:195]
	v_cvt_pk_bf16_f32 v196, v58, v59
	v_cvt_pk_bf16_f32 v197, v60, v61
	ds_write_b64 v188, v[196:197] offset:144
	v_cvt_pk_bf16_f32 v198, v46, v47
	v_cvt_pk_bf16_f32 v199, v48, v49
	ds_write_b64 v188, v[198:199] offset:32
	v_cvt_pk_bf16_f32 v200, v42, v43
	v_cvt_pk_bf16_f32 v201, v44, v45
	ds_write_b64 v188, v[200:201] offset:176
	v_cvt_pk_bf16_f32 v202, v30, v31
	v_cvt_pk_bf16_f32 v203, v32, v33
	ds_write_b64 v188, v[202:203] offset:64
	v_cvt_pk_bf16_f32 v204, v26, v27
	v_cvt_pk_bf16_f32 v205, v28, v29
	ds_write_b64 v188, v[204:205] offset:208
	v_cvt_pk_bf16_f32 v206, v14, v15
	v_cvt_pk_bf16_f32 v207, v16, v17
	ds_write_b64 v188, v[206:207] offset:96
	v_cvt_pk_bf16_f32 v208, v10, v11
	v_cvt_pk_bf16_f32 v209, v12, v13
	ds_write_b64 v188, v[208:209] offset:240
	ds_read_b128 v[152:155], v189
	ds_read_b128 v[156:159], v189 offset:1152
	ds_read_b128 v[160:163], v189 offset:2304
	ds_read_b128 v[164:167], v189 offset:3456
	s_waitcnt lgkmcnt(3)
	v_add_u32_e32 v193, 0x20000, v191
	global_store_dwordx4 v193, v[152:155], s[8:9] offset:256
	s_waitcnt lgkmcnt(2)
	v_add_u32_e32 v193, 0x20800, v191
	global_store_dwordx4 v193, v[156:159], s[8:9] offset:256
	s_waitcnt lgkmcnt(1)
	v_add_u32_e32 v193, 0x21000, v191
	global_store_dwordx4 v193, v[160:163], s[8:9] offset:256
	s_waitcnt lgkmcnt(0)
	v_add_u32_e32 v193, 0x21800, v191
	global_store_dwordx4 v193, v[164:167], s[8:9] offset:256
	s_waitcnt lgkmcnt(0)
